# all four GEMM K-loops: LDS-DMA loads use SGPR base + 32-bit VGPR offset instead of per-load 64-bit VALU address adds; epilogue and RG-LRU vmcnt fences relaxed
# speedup vs baseline: 1.0070x; 1.0005x over previous
; #define PG8_STAGE(bufoff, gbase, voff) do { _Pragma("unroll") for (int _i = 0; _i < 2; ++_i) \
;         __builtin_amdgcn_global_load_lds((const unsigned*)((const char*)(gbase) + (voff)[_i]), (PG8_LAS unsigned*)(lds + (bufoff) + ldsw + _i * 8192), 16, 0, 0); } while (0)
; #define PG8_LDA(dst, b, h) do { _Pragma("unroll") for (int m = 0; m < 4; ++m) _Pragma("unroll") for (int k = 0; k < 2; ++k) dst[m][k] = *(const PG8_LAS bf16x8*)(lds + PG8_SA(b, h) + aoff + m * 2048 + k * 1024); } while (0)
; #define PG8_LDB(dst, b, h) do { _Pragma("unroll") for (int n = 0; n < 2; ++n) _Pragma("unroll") for (int k = 0; k < 2; ++k) dst[n][k] = *(const PG8_LAS bf16x8*)(lds + PG8_SB(b, h) + boff + n * 2048 + k * 1024); } while (0)
; #define PG8_MMA(ai, bj, At, Bt) do { __builtin_amdgcn_s_setprio(1); _Pragma("unroll") for (int m = 0; m < 4; ++m) _Pragma("unroll") for (int n = 0; n < 2; ++n) _Pragma("unroll") for (int k = 0; k < 2; ++k) \
;         acc[ai][bj][m][n] = __builtin_amdgcn_mfma_f32_16x16x32_bf16(Bt[n][k], At[m][k], acc[ai][bj][m][n], 0, 0, 0); __builtin_amdgcn_s_setprio(0); } while (0)
; #define PG8_WAIT_V(n) asm volatile("s_waitcnt vmcnt(" #n ")" ::: "memory")
; #define PG8_WAIT_L(n) asm volatile("s_waitcnt lgkmcnt(" #n ")" ::: "memory")
; #define PG8_BAR __builtin_amdgcn_s_barrier()
; #define PG8_SCHED __builtin_amdgcn_sched_barrier(0)
; template <class Epi, class Sched, bool ALIGN_EPI = false, bool SP2 = false>
; __device__ __forceinline__ void gemm_phase(PG8_LAS unsigned char* lds, const Gemm g, const Sched& S, const Epi& E) {
;     ...
;             if constexpr (SP2) {
;             PG8_LDB(B0, 0, 0); PG8_LDB(B1, 0, 1); PG8_SCHED; PG8_LDA(At, 0, 0); PG8_STAGE(PG8_SA(1, 1), a1 + hstep, voffA);
;             PG8_WAIT_V(8); PG8_WAIT_L(0); PG8_BAR; PG8_MMA(0, 0, At, B0); PG8_MMA(0, 1, At, B1); PG8_BAR; PG8_SCHED;
;             PG8_LDA(At, 0, 1); PG8_STAGE(PG8_SB(0, 0), b2, voffB); PG8_STAGE(PG8_SB(0, 1), b2 + hstep, voffB); PG8_STAGE(PG8_SA(0, 0), a2, voffA);
;             PG8_WAIT_V(8); PG8_WAIT_L(0); PG8_BAR; PG8_MMA(1, 0, At, B0); PG8_MMA(1, 1, At, B1); PG8_BAR; PG8_SCHED;
.LBB0_366:
	ds_read_b128 v[130:133], v228
	ds_read_b128 v[134:137], v228 offset:1024
	ds_read_b128 v[138:141], v228 offset:2048
	ds_read_b128 v[170:173], v228 offset:3072
	ds_read_b128 v[174:177], v229
	ds_read_b128 v[178:181], v229 offset:1024
	ds_read_b128 v[182:185], v229 offset:2048
	ds_read_b128 v[186:189], v229 offset:3072
	s_add_u32 s12, s10, 0xfff00080
	s_addc_u32 s13, s11, -1
	s_cmp_eq_u32 s80, 60
	s_cselect_b32 s15, s0, s13
	s_cselect_b32 s14, s1, s12
	s_cselect_b32 s13, s61, s77
	s_cselect_b32 s12, s69, s71
	s_add_i32 m0, s79, 0xc000
	ds_read_b128 v[190:193], v230
	ds_read_b128 v[194:197], v230 offset:1024
	ds_read_b128 v[198:201], v230 offset:2048
	ds_read_b128 v[202:205], v230 offset:3072
	ds_read_b128 v[206:209], v230 offset:4096
	ds_read_b128 v[210:213], v230 offset:5120
	ds_read_b128 v[214:217], v230 offset:6144
	ds_read_b128 v[218:221], v230 offset:7168
	global_load_lds_dwordx4 v164, s[10:11]
	s_add_i32 m0, s79, 0xe000
	s_nop 0
	global_load_lds_dwordx4 v166, s[10:11]
	s_waitcnt vmcnt(8)
	s_waitcnt lgkmcnt(0)
	s_barrier
	s_setprio 1
	s_waitcnt lgkmcnt(0)
	v_mfma_f32_16x16x32_bf16 v[126:129], v[130:133], v[190:193], v[126:129]
	v_mfma_f32_16x16x32_bf16 v[122:125], v[138:141], v[190:193], v[122:125]
	v_mfma_f32_16x16x32_bf16 v[110:113], v[130:133], v[198:201], v[110:113]
	v_mfma_f32_16x16x32_bf16 v[106:109], v[138:141], v[198:201], v[106:109]
	v_mfma_f32_16x16x32_bf16 v[94:97], v[130:133], v[206:209], v[94:97]
	v_mfma_f32_16x16x32_bf16 v[90:93], v[138:141], v[206:209], v[90:93]
	v_mfma_f32_16x16x32_bf16 v[78:81], v[130:133], v[214:217], v[78:81]
	v_mfma_f32_16x16x32_bf16 v[74:77], v[138:141], v[214:217], v[74:77]
	v_mfma_f32_16x16x32_bf16 v[126:129], v[134:137], v[194:197], v[126:129]
	v_mfma_f32_16x16x32_bf16 v[122:125], v[170:173], v[194:197], v[122:125]
	v_mfma_f32_16x16x32_bf16 v[110:113], v[134:137], v[202:205], v[110:113]
	v_mfma_f32_16x16x32_bf16 v[106:109], v[170:173], v[202:205], v[106:109]
	v_mfma_f32_16x16x32_bf16 v[94:97], v[134:137], v[210:213], v[94:97]
	v_mfma_f32_16x16x32_bf16 v[90:93], v[170:173], v[210:213], v[90:93]
	v_mfma_f32_16x16x32_bf16 v[78:81], v[134:137], v[218:221], v[78:81]
	v_mfma_f32_16x16x32_bf16 v[74:77], v[170:173], v[218:221], v[74:77]
	s_setprio 0
	s_setprio 1
	v_mfma_f32_16x16x32_bf16 v[118:121], v[174:177], v[190:193], v[118:121]
	v_mfma_f32_16x16x32_bf16 v[114:117], v[182:185], v[190:193], v[114:117]
	v_mfma_f32_16x16x32_bf16 v[102:105], v[174:177], v[198:201], v[102:105]
	v_mfma_f32_16x16x32_bf16 v[98:101], v[182:185], v[198:201], v[98:101]
	v_mfma_f32_16x16x32_bf16 v[86:89], v[174:177], v[206:209], v[86:89]
	v_mfma_f32_16x16x32_bf16 v[82:85], v[182:185], v[206:209], v[82:85]
	v_mfma_f32_16x16x32_bf16 v[70:73], v[174:177], v[214:217], v[70:73]
	v_mfma_f32_16x16x32_bf16 v[66:69], v[182:185], v[214:217], v[66:69]
	v_mfma_f32_16x16x32_bf16 v[118:121], v[178:181], v[194:197], v[118:121]
	v_mfma_f32_16x16x32_bf16 v[114:117], v[186:189], v[194:197], v[114:117]
	v_mfma_f32_16x16x32_bf16 v[102:105], v[178:181], v[202:205], v[102:105]
	v_mfma_f32_16x16x32_bf16 v[98:101], v[186:189], v[202:205], v[98:101]
	v_mfma_f32_16x16x32_bf16 v[86:89], v[178:181], v[210:213], v[86:89]
	v_mfma_f32_16x16x32_bf16 v[82:85], v[186:189], v[210:213], v[82:85]
	v_mfma_f32_16x16x32_bf16 v[70:73], v[178:181], v[218:221], v[70:73]
	v_mfma_f32_16x16x32_bf16 v[66:69], v[186:189], v[218:221], v[66:69]
	s_setprio 0
	s_barrier
	s_add_i32 s81, s63, s67
	s_mov_b32 m0, s81
	ds_read_b128 v[190:193], v230 offset:16384
	ds_read_b128 v[194:197], v230 offset:17408
	ds_read_b128 v[198:201], v230 offset:18432
	ds_read_b128 v[202:205], v230 offset:19456
	ds_read_b128 v[206:209], v230 offset:20480
	ds_read_b128 v[210:213], v230 offset:21504
	ds_read_b128 v[214:217], v230 offset:22528
	ds_read_b128 v[218:221], v230 offset:23552
	global_load_lds_dwordx4 v144, s[12:13]
	s_add_i32 m0, s81, 0x2000
	s_add_u32 s82, s12, 0x100000
	s_addc_u32 s83, s13, 0
	s_add_i32 s81, s94, s67
	global_load_lds_dwordx4 v148, s[12:13]
	s_mov_b32 m0, s81
	s_nop 0
	global_load_lds_dwordx4 v144, s[82:83]
	s_add_i32 m0, s81, 0x2000
	s_nop 0
	global_load_lds_dwordx4 v148, s[82:83]
	s_mov_b32 m0, s79
	s_nop 0
	global_load_lds_dwordx4 v142, s[14:15]
	s_mov_b32 m0, s88
	s_nop 0
	global_load_lds_dwordx4 v146, s[14:15]
	s_waitcnt vmcnt(8)
	s_waitcnt lgkmcnt(0)
	s_barrier
	s_setprio 1
	s_waitcnt lgkmcnt(0)
	v_mfma_f32_16x16x32_bf16 v[62:65], v[130:133], v[190:193], v[62:65]
	v_mfma_f32_16x16x32_bf16 v[58:61], v[138:141], v[190:193], v[58:61]
	v_mfma_f32_16x16x32_bf16 v[46:49], v[130:133], v[198:201], v[46:49]
	v_mfma_f32_16x16x32_bf16 v[42:45], v[138:141], v[198:201], v[42:45]
	v_mfma_f32_16x16x32_bf16 v[30:33], v[130:133], v[206:209], v[30:33]
	v_mfma_f32_16x16x32_bf16 v[26:29], v[138:141], v[206:209], v[26:29]
	v_mfma_f32_16x16x32_bf16 v[14:17], v[130:133], v[214:217], v[14:17]
	v_mfma_f32_16x16x32_bf16 v[10:13], v[138:141], v[214:217], v[10:13]
	v_mfma_f32_16x16x32_bf16 v[62:65], v[134:137], v[194:197], v[62:65]
	v_mfma_f32_16x16x32_bf16 v[58:61], v[170:173], v[194:197], v[58:61]
	v_mfma_f32_16x16x32_bf16 v[46:49], v[134:137], v[202:205], v[46:49]
	v_mfma_f32_16x16x32_bf16 v[42:45], v[170:173], v[202:205], v[42:45]
	v_mfma_f32_16x16x32_bf16 v[30:33], v[134:137], v[210:213], v[30:33]
	v_mfma_f32_16x16x32_bf16 v[26:29], v[170:173], v[210:213], v[26:29]
	v_mfma_f32_16x16x32_bf16 v[14:17], v[134:137], v[218:221], v[14:17]
	v_mfma_f32_16x16x32_bf16 v[10:13], v[170:173], v[218:221], v[10:13]
	s_setprio 0
	s_setprio 1
	v_mfma_f32_16x16x32_bf16 v[54:57], v[174:177], v[190:193], v[54:57]
	v_mfma_f32_16x16x32_bf16 v[50:53], v[182:185], v[190:193], v[50:53]
	v_mfma_f32_16x16x32_bf16 v[38:41], v[174:177], v[198:201], v[38:41]
	v_mfma_f32_16x16x32_bf16 v[34:37], v[182:185], v[198:201], v[34:37]
	v_mfma_f32_16x16x32_bf16 v[22:25], v[174:177], v[206:209], v[22:25]
	v_mfma_f32_16x16x32_bf16 v[18:21], v[182:185], v[206:209], v[18:21]
	v_mfma_f32_16x16x32_bf16 v[6:9], v[174:177], v[214:217], v[6:9]
	v_mfma_f32_16x16x32_bf16 v[2:5], v[182:185], v[214:217], v[2:5]
	v_mfma_f32_16x16x32_bf16 v[54:57], v[178:181], v[194:197], v[54:57]
	v_mfma_f32_16x16x32_bf16 v[50:53], v[186:189], v[194:197], v[50:53]
	v_mfma_f32_16x16x32_bf16 v[38:41], v[178:181], v[202:205], v[38:41]
	v_mfma_f32_16x16x32_bf16 v[34:37], v[186:189], v[202:205], v[34:37]
	v_mfma_f32_16x16x32_bf16 v[22:25], v[178:181], v[210:213], v[22:25]
	v_mfma_f32_16x16x32_bf16 v[18:21], v[186:189], v[210:213], v[18:21]
	v_mfma_f32_16x16x32_bf16 v[6:9], v[178:181], v[218:221], v[6:9]
	v_mfma_f32_16x16x32_bf16 v[2:5], v[186:189], v[218:221], v[2:5]
	s_setprio 0
	s_barrier
; #define PG8_STAGE(bufoff, gbase, voff) do { _Pragma("unroll") for (int _i = 0; _i < 2; ++_i) \
;         __builtin_amdgcn_global_load_lds((const unsigned*)((const char*)(gbase) + (voff)[_i]), (PG8_LAS unsigned*)(lds + (bufoff) + ldsw + _i * 8192), 16, 0, 0); } while (0)
; #define PG8_LDA(dst, b, h) do { _Pragma("unroll") for (int m = 0; m < 4; ++m) _Pragma("unroll") for (int k = 0; k < 2; ++k) dst[m][k] = *(const PG8_LAS bf16x8*)(lds + PG8_SA(b, h) + aoff + m * 2048 + k * 1024); } while (0)
; #define PG8_LDB(dst, b, h) do { _Pragma("unroll") for (int n = 0; n < 2; ++n) _Pragma("unroll") for (int k = 0; k < 2; ++k) dst[n][k] = *(const PG8_LAS bf16x8*)(lds + PG8_SB(b, h) + boff + n * 2048 + k * 1024); } while (0)
; #define PG8_MMA(ai, bj, At, Bt) do { __builtin_amdgcn_s_setprio(1); _Pragma("unroll") for (int m = 0; m < 4; ++m) _Pragma("unroll") for (int n = 0; n < 2; ++n) _Pragma("unroll") for (int k = 0; k < 2; ++k) \
;         acc[ai][bj][m][n] = __builtin_amdgcn_mfma_f32_16x16x32_bf16(Bt[n][k], At[m][k], acc[ai][bj][m][n], 0, 0, 0); __builtin_amdgcn_s_setprio(0); } while (0)
; #define PG8_WAIT_V(n) asm volatile("s_waitcnt vmcnt(" #n ")" ::: "memory")
; template <class Epi, class Sched, bool ALIGN_EPI = false, bool SP2 = false>
; __device__ __forceinline__ void gemm_phase(PG8_LAS unsigned char* lds, const Gemm g, const Sched& S, const Epi& E) {
;     ...
;         for (int t = 0; t < ntc; t += 2) {
;             if constexpr (Epi::MID) { if (ntc == nt && t == (nt >> 1)) E.mid(acc, cur, wr, wc, fr, fq); }
;             const bool last = (t == ntc - 2);
;             const char* a1 = cA + (size_t)(t + 1) * kstep;
;             const char* a2 = last ? nA : cA + (size_t)(t + 2) * kstep; const char* b2 = last ? nB : cB + (size_t)(t + 2) * kstep;
;             const char* a3 = a2 + kstep; const char* b3 = b2 + kstep;
;             if (last && has_next) S.a_ready(nxt);
;     ...
;             PG8_LDB(B0, 1, 0); PG8_LDB(B1, 1, 1); PG8_SCHED; PG8_LDA(At, 1, 0); PG8_STAGE(PG8_SA(0, 1), a2 + hstep, voffA);
;             PG8_WAIT_V(8); PG8_WAIT_L(0); PG8_BAR; PG8_MMA(0, 0, At, B0); PG8_MMA(0, 1, At, B1); PG8_BAR; PG8_SCHED;
;             PG8_LDA(At, 1, 1); PG8_STAGE(PG8_SB(1, 0), b3, voffB); PG8_STAGE(PG8_SB(1, 1), b3 + hstep, voffB); PG8_STAGE(PG8_SA(1, 0), a3, voffA);
;             PG8_WAIT_V(8); PG8_WAIT_L(0); PG8_BAR; PG8_MMA(1, 0, At, B0); PG8_MMA(1, 1, At, B1); PG8_BAR; PG8_SCHED;
	s_add_i32 s81, 0, 0x18000
	v_add_u32_e32 v150, s81, v153
	s_add_i32 s82, 0, 0x1c000
	ds_read_b128 v[130:133], v150
	ds_read_b128 v[134:137], v150 offset:1024
	ds_read_b128 v[138:141], v150 offset:2048
	ds_read_b128 v[170:173], v150 offset:3072
	v_add_u32_e32 v150, s82, v153
	ds_read_b128 v[174:177], v150
	ds_read_b128 v[178:181], v150 offset:1024
	ds_read_b128 v[182:185], v150 offset:2048
	ds_read_b128 v[186:189], v150 offset:3072
	s_add_u32 s14, s14, 0x100000
	s_addc_u32 s15, s15, 0
	s_mov_b32 m0, s89
	ds_read_b128 v[190:193], v230 offset:32768
	ds_read_b128 v[194:197], v230 offset:33792
	ds_read_b128 v[198:201], v230 offset:34816
	ds_read_b128 v[202:205], v230 offset:35840
	ds_read_b128 v[206:209], v230 offset:36864
	ds_read_b128 v[210:213], v230 offset:37888
	ds_read_b128 v[214:217], v230 offset:38912
	ds_read_b128 v[218:221], v230 offset:39936
	global_load_lds_dwordx4 v142, s[14:15]
	s_mov_b32 m0, s90
	s_nop 0
	global_load_lds_dwordx4 v146, s[14:15]
	s_waitcnt vmcnt(8)
	s_waitcnt lgkmcnt(0)
	s_barrier
	s_setprio 1
	s_waitcnt lgkmcnt(0)
	v_mfma_f32_16x16x32_bf16 v[126:129], v[130:133], v[190:193], v[126:129]
	v_mfma_f32_16x16x32_bf16 v[122:125], v[138:141], v[190:193], v[122:125]
	v_mfma_f32_16x16x32_bf16 v[110:113], v[130:133], v[198:201], v[110:113]
	v_mfma_f32_16x16x32_bf16 v[106:109], v[138:141], v[198:201], v[106:109]
	v_mfma_f32_16x16x32_bf16 v[94:97], v[130:133], v[206:209], v[94:97]
	v_mfma_f32_16x16x32_bf16 v[90:93], v[138:141], v[206:209], v[90:93]
	v_mfma_f32_16x16x32_bf16 v[78:81], v[130:133], v[214:217], v[78:81]
	v_mfma_f32_16x16x32_bf16 v[74:77], v[138:141], v[214:217], v[74:77]
	v_mfma_f32_16x16x32_bf16 v[126:129], v[134:137], v[194:197], v[126:129]
	v_mfma_f32_16x16x32_bf16 v[122:125], v[170:173], v[194:197], v[122:125]
	v_mfma_f32_16x16x32_bf16 v[110:113], v[134:137], v[202:205], v[110:113]
	v_mfma_f32_16x16x32_bf16 v[106:109], v[170:173], v[202:205], v[106:109]
	v_mfma_f32_16x16x32_bf16 v[94:97], v[134:137], v[210:213], v[94:97]
	v_mfma_f32_16x16x32_bf16 v[90:93], v[170:173], v[210:213], v[90:93]
	v_mfma_f32_16x16x32_bf16 v[78:81], v[134:137], v[218:221], v[78:81]
	v_mfma_f32_16x16x32_bf16 v[74:77], v[170:173], v[218:221], v[74:77]
	s_setprio 0
	s_setprio 1
	v_mfma_f32_16x16x32_bf16 v[118:121], v[174:177], v[190:193], v[118:121]
	v_mfma_f32_16x16x32_bf16 v[114:117], v[182:185], v[190:193], v[114:117]
	v_mfma_f32_16x16x32_bf16 v[102:105], v[174:177], v[198:201], v[102:105]
	v_mfma_f32_16x16x32_bf16 v[98:101], v[182:185], v[198:201], v[98:101]
	v_mfma_f32_16x16x32_bf16 v[86:89], v[174:177], v[206:209], v[86:89]
	v_mfma_f32_16x16x32_bf16 v[82:85], v[182:185], v[206:209], v[82:85]
	v_mfma_f32_16x16x32_bf16 v[70:73], v[174:177], v[214:217], v[70:73]
	v_mfma_f32_16x16x32_bf16 v[66:69], v[182:185], v[214:217], v[66:69]
	v_mfma_f32_16x16x32_bf16 v[118:121], v[178:181], v[194:197], v[118:121]
	v_mfma_f32_16x16x32_bf16 v[114:117], v[186:189], v[194:197], v[114:117]
	v_mfma_f32_16x16x32_bf16 v[102:105], v[178:181], v[202:205], v[102:105]
	v_mfma_f32_16x16x32_bf16 v[98:101], v[186:189], v[202:205], v[98:101]
	v_mfma_f32_16x16x32_bf16 v[86:89], v[178:181], v[210:213], v[86:89]
	v_mfma_f32_16x16x32_bf16 v[82:85], v[186:189], v[210:213], v[82:85]
	v_mfma_f32_16x16x32_bf16 v[70:73], v[178:181], v[218:221], v[70:73]
	v_mfma_f32_16x16x32_bf16 v[66:69], v[186:189], v[218:221], v[66:69]
	s_setprio 0
	s_barrier
	s_add_u32 s100, s14, 0xfff00080
	s_addc_u32 s101, s15, -1
	s_add_u32 s98, s12, 0x80
	s_addc_u32 s99, s13, 0
	s_add_i32 s14, s81, s67
	s_mov_b32 m0, s14
	ds_read_b128 v[190:193], v230 offset:49152
	ds_read_b128 v[194:197], v230 offset:50176
	ds_read_b128 v[198:201], v230 offset:51200
	ds_read_b128 v[202:205], v230 offset:52224
	ds_read_b128 v[206:209], v230 offset:53248
	ds_read_b128 v[210:213], v230 offset:54272
	ds_read_b128 v[214:217], v230 offset:55296
	ds_read_b128 v[218:221], v230 offset:56320
	global_load_lds_dwordx4 v144, s[98:99]
	s_add_i32 m0, s14, 0x2000
	s_add_u32 s12, s12, 0x100080
	s_addc_u32 s13, s13, 0
	s_add_i32 s14, s82, s67
	global_load_lds_dwordx4 v148, s[98:99]
	s_mov_b32 m0, s14
	s_nop 0
	global_load_lds_dwordx4 v144, s[12:13]
	s_add_i32 m0, s14, 0x2000
	s_nop 0
	global_load_lds_dwordx4 v148, s[12:13]
	s_mov_b32 m0, s93
	s_nop 0
	global_load_lds_dwordx4 v142, s[100:101]
	s_mov_b32 m0, s62
	s_nop 0
	global_load_lds_dwordx4 v146, s[100:101]
	s_waitcnt vmcnt(8)
	s_waitcnt lgkmcnt(0)
	s_barrier
	s_setprio 1
	s_waitcnt lgkmcnt(0)
	v_mfma_f32_16x16x32_bf16 v[62:65], v[130:133], v[190:193], v[62:65]
	v_mfma_f32_16x16x32_bf16 v[58:61], v[138:141], v[190:193], v[58:61]
	v_mfma_f32_16x16x32_bf16 v[46:49], v[130:133], v[198:201], v[46:49]
	v_mfma_f32_16x16x32_bf16 v[42:45], v[138:141], v[198:201], v[42:45]
	v_mfma_f32_16x16x32_bf16 v[30:33], v[130:133], v[206:209], v[30:33]
	v_mfma_f32_16x16x32_bf16 v[26:29], v[138:141], v[206:209], v[26:29]
	v_mfma_f32_16x16x32_bf16 v[14:17], v[130:133], v[214:217], v[14:17]
	v_mfma_f32_16x16x32_bf16 v[10:13], v[138:141], v[214:217], v[10:13]
	v_mfma_f32_16x16x32_bf16 v[62:65], v[134:137], v[194:197], v[62:65]
	v_mfma_f32_16x16x32_bf16 v[58:61], v[170:173], v[194:197], v[58:61]
	v_mfma_f32_16x16x32_bf16 v[46:49], v[134:137], v[202:205], v[46:49]
	v_mfma_f32_16x16x32_bf16 v[42:45], v[170:173], v[202:205], v[42:45]
	v_mfma_f32_16x16x32_bf16 v[30:33], v[134:137], v[210:213], v[30:33]
	v_mfma_f32_16x16x32_bf16 v[26:29], v[170:173], v[210:213], v[26:29]
	v_mfma_f32_16x16x32_bf16 v[14:17], v[134:137], v[218:221], v[14:17]
	v_mfma_f32_16x16x32_bf16 v[10:13], v[170:173], v[218:221], v[10:13]
	s_setprio 0
	s_setprio 1
	v_mfma_f32_16x16x32_bf16 v[54:57], v[174:177], v[190:193], v[54:57]
	v_mfma_f32_16x16x32_bf16 v[50:53], v[182:185], v[190:193], v[50:53]
	v_mfma_f32_16x16x32_bf16 v[38:41], v[174:177], v[198:201], v[38:41]
	v_mfma_f32_16x16x32_bf16 v[34:37], v[182:185], v[198:201], v[34:37]
	v_mfma_f32_16x16x32_bf16 v[22:25], v[174:177], v[206:209], v[22:25]
	v_mfma_f32_16x16x32_bf16 v[18:21], v[182:185], v[206:209], v[18:21]
	v_mfma_f32_16x16x32_bf16 v[6:9], v[174:177], v[214:217], v[6:9]
	v_mfma_f32_16x16x32_bf16 v[2:5], v[182:185], v[214:217], v[2:5]
	v_mfma_f32_16x16x32_bf16 v[54:57], v[178:181], v[194:197], v[54:57]
	v_mfma_f32_16x16x32_bf16 v[50:53], v[186:189], v[194:197], v[50:53]
	v_mfma_f32_16x16x32_bf16 v[38:41], v[178:181], v[202:205], v[38:41]
	v_mfma_f32_16x16x32_bf16 v[34:37], v[186:189], v[202:205], v[34:37]
	v_mfma_f32_16x16x32_bf16 v[22:25], v[178:181], v[210:213], v[22:25]
	v_mfma_f32_16x16x32_bf16 v[18:21], v[186:189], v[210:213], v[18:21]
	v_mfma_f32_16x16x32_bf16 v[6:9], v[178:181], v[218:221], v[6:9]
	v_mfma_f32_16x16x32_bf16 v[2:5], v[186:189], v[218:221], v[2:5]
	s_setprio 0
	s_barrier
	s_add_i32 s80, s80, 2
	s_add_u32 s10, s10, 0x100
	s_addc_u32 s11, s11, 0
	s_add_u32 s71, s71, 0x100
	s_addc_u32 s77, s77, 0
	s_cmp_gt_u32 s80, 61
	s_cbranch_scc0 .LBB0_366
	s_and_b64 vcc, exec, s[28:29]
	s_cbranch_vccz .LBB0_369
	s_barrier

; #define PG8_STAGE(bufoff, gbase, voff) do { _Pragma("unroll") for (int _i = 0; _i < 2; ++_i) \
;         __builtin_amdgcn_global_load_lds((const unsigned*)((const char*)(gbase) + (voff)[_i]), (PG8_LAS unsigned*)(lds + (bufoff) + ldsw + _i * 8192), 16, 0, 0); } while (0)
; #define PG8_LDA(dst, b, h) do { _Pragma("unroll") for (int m = 0; m < 4; ++m) _Pragma("unroll") for (int k = 0; k < 2; ++k) dst[m][k] = *(const PG8_LAS bf16x8*)(lds + PG8_SA(b, h) + aoff + m * 2048 + k * 1024); } while (0)
; #define PG8_LDB(dst, b, h) do { _Pragma("unroll") for (int n = 0; n < 2; ++n) _Pragma("unroll") for (int k = 0; k < 2; ++k) dst[n][k] = *(const PG8_LAS bf16x8*)(lds + PG8_SB(b, h) + boff + n * 2048 + k * 1024); } while (0)
; #define PG8_MMA(ai, bj, At, Bt) do { __builtin_amdgcn_s_setprio(1); _Pragma("unroll") for (int m = 0; m < 4; ++m) _Pragma("unroll") for (int n = 0; n < 2; ++n) _Pragma("unroll") for (int k = 0; k < 2; ++k) \
;         acc[ai][bj][m][n] = __builtin_amdgcn_mfma_f32_16x16x32_bf16(Bt[n][k], At[m][k], acc[ai][bj][m][n], 0, 0, 0); __builtin_amdgcn_s_setprio(0); } while (0)
; template <class Epi, class Sched, bool ALIGN_EPI = false, bool SP2 = false>
; __device__ __forceinline__ void gemm_phase(PG8_LAS unsigned char* lds, const Gemm g, const Sched& S, const Epi& E) {
;     ...
;         for (int t = 0; t < ntc; t += 2) {
;             if constexpr (Epi::MID) { if (ntc == nt && t == (nt >> 1)) E.mid(acc, cur, wr, wc, fr, fq); }
;             const bool last = (t == ntc - 2);
;             const char* a1 = cA + (size_t)(t + 1) * kstep;
;             const char* a2 = last ? nA : cA + (size_t)(t + 2) * kstep; const char* b2 = last ? nB : cB + (size_t)(t + 2) * kstep;
;             const char* a3 = a2 + kstep; const char* b3 = b2 + kstep;
;             if (last && has_next) S.a_ready(nxt);
;             if constexpr (SP2) {
;             PG8_LDB(B0, 0, 0); PG8_LDB(B1, 0, 1); PG8_SCHED; PG8_LDA(At, 0, 0); PG8_STAGE(PG8_SA(1, 1), a1 + hstep, voffA);
;             PG8_WAIT_V(8); PG8_WAIT_L(0); PG8_BAR; PG8_MMA(0, 0, At, B0); PG8_MMA(0, 1, At, B1); PG8_BAR; PG8_SCHED;
;             PG8_LDA(At, 0, 1); PG8_STAGE(PG8_SB(0, 0), b2, voffB); PG8_STAGE(PG8_SB(0, 1), b2 + hstep, voffB); PG8_STAGE(PG8_SA(0, 0), a2, voffA);
;             PG8_WAIT_V(8); PG8_WAIT_L(0); PG8_BAR; PG8_MMA(1, 0, At, B0); PG8_MMA(1, 1, At, B1); PG8_BAR; PG8_SCHED;
.LBB0_2487:
	v_add_u32_e32 v3, s67, v183
	s_add_i32 s81, s50, 2
	ds_read_b128 v[154:157], v3
	ds_read_b128 v[158:161], v3 offset:1024
	ds_read_b128 v[162:165], v3 offset:2048
	ds_read_b128 v[166:169], v3 offset:3072
	v_add_u32_e32 v3, s68, v183
	s_add_u32 s51, s42, s46
	ds_read_b128 v[170:173], v3
	ds_read_b128 v[174:177], v3 offset:1024
	ds_read_b128 v[178:181], v3 offset:2048
	ds_read_b128 v[184:187], v3 offset:3072
	s_addc_u32 s52, s43, s47
	s_add_u32 s51, s51, 0x100
	s_addc_u32 s52, s52, 0
	s_add_u32 s82, s79, s46
	s_addc_u32 s83, s80, s47
	s_cmp_eq_u32 s9, s50
	s_cselect_b32 s53, s27, s52
	s_cselect_b32 s52, s35, s51
	s_cselect_b32 s51, s31, s83
	s_cselect_b32 s50, s78, s82
	v_lshl_add_u64 v[4:5], v[150:151], 0, s[46:47]
	s_add_i32 m0, s11, 0xc000
	ds_read_b128 v[188:191], v211
	ds_read_b128 v[192:195], v211 offset:1024
	ds_read_b128 v[196:199], v211 offset:2048
	ds_read_b128 v[200:203], v211 offset:3072
	ds_read_b128 v[204:207], v211 offset:4096
	ds_read_b128 v[212:215], v211 offset:5120
	ds_read_b128 v[216:219], v211 offset:6144
	ds_read_b128 v[220:223], v211 offset:7168
	global_load_lds_dwordx4 v[4:5], off
	v_lshl_add_u64 v[4:5], v[152:153], 0, s[46:47]
	s_add_i32 m0, s11, 0xe000
	s_nop 0
	global_load_lds_dwordx4 v[4:5], off
	s_waitcnt vmcnt(8)
	s_waitcnt lgkmcnt(0)
	s_barrier
	s_setprio 1
	s_waitcnt lgkmcnt(0)
	v_mfma_f32_16x16x32_bf16 v[130:133], v[154:157], v[188:191], v[130:133]
	v_mfma_f32_16x16x32_bf16 v[126:129], v[162:165], v[188:191], v[126:129]
	v_mfma_f32_16x16x32_bf16 v[114:117], v[154:157], v[196:199], v[114:117]
	v_mfma_f32_16x16x32_bf16 v[110:113], v[162:165], v[196:199], v[110:113]
	v_mfma_f32_16x16x32_bf16 v[98:101], v[154:157], v[204:207], v[98:101]
	v_mfma_f32_16x16x32_bf16 v[94:97], v[162:165], v[204:207], v[94:97]
	v_mfma_f32_16x16x32_bf16 v[82:85], v[154:157], v[216:219], v[82:85]
	v_mfma_f32_16x16x32_bf16 v[78:81], v[162:165], v[216:219], v[78:81]
	v_mfma_f32_16x16x32_bf16 v[130:133], v[158:161], v[192:195], v[130:133]
	v_mfma_f32_16x16x32_bf16 v[126:129], v[166:169], v[192:195], v[126:129]
	v_mfma_f32_16x16x32_bf16 v[114:117], v[158:161], v[200:203], v[114:117]
	v_mfma_f32_16x16x32_bf16 v[110:113], v[166:169], v[200:203], v[110:113]
	v_mfma_f32_16x16x32_bf16 v[98:101], v[158:161], v[212:215], v[98:101]
	v_mfma_f32_16x16x32_bf16 v[94:97], v[166:169], v[212:215], v[94:97]
	v_mfma_f32_16x16x32_bf16 v[82:85], v[158:161], v[220:223], v[82:85]
	v_mfma_f32_16x16x32_bf16 v[78:81], v[166:169], v[220:223], v[78:81]
	s_setprio 0
	s_setprio 1
	v_mfma_f32_16x16x32_bf16 v[122:125], v[170:173], v[188:191], v[122:125]
	v_mfma_f32_16x16x32_bf16 v[118:121], v[178:181], v[188:191], v[118:121]
	v_mfma_f32_16x16x32_bf16 v[106:109], v[170:173], v[196:199], v[106:109]
	v_mfma_f32_16x16x32_bf16 v[102:105], v[178:181], v[196:199], v[102:105]
	v_mfma_f32_16x16x32_bf16 v[90:93], v[170:173], v[204:207], v[90:93]
	v_mfma_f32_16x16x32_bf16 v[86:89], v[178:181], v[204:207], v[86:89]
	v_mfma_f32_16x16x32_bf16 v[74:77], v[170:173], v[216:219], v[74:77]
	v_mfma_f32_16x16x32_bf16 v[70:73], v[178:181], v[216:219], v[70:73]
	v_mfma_f32_16x16x32_bf16 v[122:125], v[174:177], v[192:195], v[122:125]
	v_mfma_f32_16x16x32_bf16 v[118:121], v[184:187], v[192:195], v[118:121]
	v_mfma_f32_16x16x32_bf16 v[106:109], v[174:177], v[200:203], v[106:109]
	v_mfma_f32_16x16x32_bf16 v[102:105], v[184:187], v[200:203], v[102:105]
	v_mfma_f32_16x16x32_bf16 v[90:93], v[174:177], v[212:215], v[90:93]
	v_mfma_f32_16x16x32_bf16 v[86:89], v[184:187], v[212:215], v[86:89]
	v_mfma_f32_16x16x32_bf16 v[74:77], v[174:177], v[220:223], v[74:77]
	v_mfma_f32_16x16x32_bf16 v[70:73], v[184:187], v[220:223], v[70:73]
	s_setprio 0
	s_barrier
	s_add_i32 s82, s67, s55
	s_mov_b32 m0, s82
	ds_read_b128 v[188:191], v211 offset:16384
	ds_read_b128 v[192:195], v211 offset:17408
	ds_read_b128 v[196:199], v211 offset:18432
	ds_read_b128 v[200:203], v211 offset:19456
	ds_read_b128 v[204:207], v211 offset:20480
	ds_read_b128 v[212:215], v211 offset:21504
	ds_read_b128 v[216:219], v211 offset:22528
	ds_read_b128 v[220:223], v211 offset:23552
	global_load_lds_dwordx4 v134, s[50:51]
	s_add_i32 m0, s82, 0x2000
	s_add_u32 s82, s50, 0x100000
	s_addc_u32 s83, s51, 0
	s_add_i32 s84, s68, s55
	global_load_lds_dwordx4 v136, s[50:51]
	s_mov_b32 m0, s84
	s_nop 0
	global_load_lds_dwordx4 v134, s[82:83]
	s_add_i32 m0, s84, 0x2000
	s_nop 0
	global_load_lds_dwordx4 v136, s[82:83]
	s_mov_b32 m0, s11
	s_nop 0
	global_load_lds_dwordx4 v134, s[52:53]
	s_mov_b32 m0, s57
	s_nop 0
	global_load_lds_dwordx4 v136, s[52:53]
	s_waitcnt vmcnt(8)
	s_waitcnt lgkmcnt(0)
	s_barrier
; #define PG8_STAGE(bufoff, gbase, voff) do { _Pragma("unroll") for (int _i = 0; _i < 2; ++_i) \
;         __builtin_amdgcn_global_load_lds((const unsigned*)((const char*)(gbase) + (voff)[_i]), (PG8_LAS unsigned*)(lds + (bufoff) + ldsw + _i * 8192), 16, 0, 0); } while (0)
; #define PG8_LDA(dst, b, h) do { _Pragma("unroll") for (int m = 0; m < 4; ++m) _Pragma("unroll") for (int k = 0; k < 2; ++k) dst[m][k] = *(const PG8_LAS bf16x8*)(lds + PG8_SA(b, h) + aoff + m * 2048 + k * 1024); } while (0)
; #define PG8_LDB(dst, b, h) do { _Pragma("unroll") for (int n = 0; n < 2; ++n) _Pragma("unroll") for (int k = 0; k < 2; ++k) dst[n][k] = *(const PG8_LAS bf16x8*)(lds + PG8_SB(b, h) + boff + n * 2048 + k * 1024); } while (0)
; #define PG8_MMA(ai, bj, At, Bt) do { __builtin_amdgcn_s_setprio(1); _Pragma("unroll") for (int m = 0; m < 4; ++m) _Pragma("unroll") for (int n = 0; n < 2; ++n) _Pragma("unroll") for (int k = 0; k < 2; ++k) \
;         acc[ai][bj][m][n] = __builtin_amdgcn_mfma_f32_16x16x32_bf16(Bt[n][k], At[m][k], acc[ai][bj][m][n], 0, 0, 0); __builtin_amdgcn_s_setprio(0); } while (0)
; #define PG8_WAIT_V(n) asm volatile("s_waitcnt vmcnt(" #n ")" ::: "memory")
; #define PG8_WAIT_L(n) asm volatile("s_waitcnt lgkmcnt(" #n ")" ::: "memory")
; #define PG8_BAR __builtin_amdgcn_s_barrier()
; #define PG8_SCHED __builtin_amdgcn_sched_barrier(0)
; template <class Epi, class Sched, bool ALIGN_EPI = false, bool SP2 = false>
; __device__ __forceinline__ void gemm_phase(PG8_LAS unsigned char* lds, const Gemm g, const Sched& S, const Epi& E) {
;     ...
;             PG8_LDA(At, 0, 1); PG8_STAGE(PG8_SB(0, 0), b2, voffB); PG8_STAGE(PG8_SB(0, 1), b2 + hstep, voffB); PG8_STAGE(PG8_SA(0, 0), a2, voffA);
;             PG8_WAIT_V(8); PG8_WAIT_L(0); PG8_BAR; PG8_MMA(1, 0, At, B0); PG8_MMA(1, 1, At, B1); PG8_BAR; PG8_SCHED;
;             PG8_LDB(B0, 1, 0); PG8_LDB(B1, 1, 1); PG8_SCHED; PG8_LDA(At, 1, 0); PG8_STAGE(PG8_SA(0, 1), a2 + hstep, voffA);
;             PG8_WAIT_V(8); PG8_WAIT_L(0); PG8_BAR; PG8_MMA(0, 0, At, B0); PG8_MMA(0, 1, At, B1); PG8_BAR; PG8_SCHED;
;             PG8_LDA(At, 1, 1); PG8_STAGE(PG8_SB(1, 0), b3, voffB); PG8_STAGE(PG8_SB(1, 1), b3 + hstep, voffB); PG8_STAGE(PG8_SA(1, 0), a3, voffA);
	s_setprio 1
	s_waitcnt lgkmcnt(0)
	v_mfma_f32_16x16x32_bf16 v[66:69], v[154:157], v[188:191], v[66:69]
	v_mfma_f32_16x16x32_bf16 v[62:65], v[162:165], v[188:191], v[62:65]
	v_mfma_f32_16x16x32_bf16 v[50:53], v[154:157], v[196:199], v[50:53]
	v_mfma_f32_16x16x32_bf16 v[46:49], v[162:165], v[196:199], v[46:49]
	v_mfma_f32_16x16x32_bf16 v[34:37], v[154:157], v[204:207], v[34:37]
	v_mfma_f32_16x16x32_bf16 v[30:33], v[162:165], v[204:207], v[30:33]
	v_mfma_f32_16x16x32_bf16 v[18:21], v[154:157], v[216:219], v[18:21]
	v_mfma_f32_16x16x32_bf16 v[14:17], v[162:165], v[216:219], v[14:17]
	v_mfma_f32_16x16x32_bf16 v[66:69], v[158:161], v[192:195], v[66:69]
	v_mfma_f32_16x16x32_bf16 v[62:65], v[166:169], v[192:195], v[62:65]
	v_mfma_f32_16x16x32_bf16 v[50:53], v[158:161], v[200:203], v[50:53]
	v_mfma_f32_16x16x32_bf16 v[46:49], v[166:169], v[200:203], v[46:49]
	v_mfma_f32_16x16x32_bf16 v[34:37], v[158:161], v[212:215], v[34:37]
	v_mfma_f32_16x16x32_bf16 v[30:33], v[166:169], v[212:215], v[30:33]
	v_mfma_f32_16x16x32_bf16 v[18:21], v[158:161], v[220:223], v[18:21]
	v_mfma_f32_16x16x32_bf16 v[14:17], v[166:169], v[220:223], v[14:17]
	s_setprio 0
	s_setprio 1
	v_mfma_f32_16x16x32_bf16 v[58:61], v[170:173], v[188:191], v[58:61]
	v_mfma_f32_16x16x32_bf16 v[54:57], v[178:181], v[188:191], v[54:57]
	v_mfma_f32_16x16x32_bf16 v[42:45], v[170:173], v[196:199], v[42:45]
	v_mfma_f32_16x16x32_bf16 v[38:41], v[178:181], v[196:199], v[38:41]
	v_mfma_f32_16x16x32_bf16 v[26:29], v[170:173], v[204:207], v[26:29]
	v_mfma_f32_16x16x32_bf16 v[22:25], v[178:181], v[204:207], v[22:25]
	v_mfma_f32_16x16x32_bf16 v[10:13], v[170:173], v[216:219], v[10:13]
	v_mfma_f32_16x16x32_bf16 v[4:7], v[178:181], v[216:219], v[6:9]
	v_mfma_f32_16x16x32_bf16 v[58:61], v[174:177], v[192:195], v[58:61]
	v_mfma_f32_16x16x32_bf16 v[54:57], v[184:187], v[192:195], v[54:57]
	v_mfma_f32_16x16x32_bf16 v[42:45], v[174:177], v[200:203], v[42:45]
	v_mfma_f32_16x16x32_bf16 v[38:41], v[184:187], v[200:203], v[38:41]
	v_mfma_f32_16x16x32_bf16 v[26:29], v[174:177], v[212:215], v[26:29]
	v_mfma_f32_16x16x32_bf16 v[22:25], v[184:187], v[212:215], v[22:25]
	v_mfma_f32_16x16x32_bf16 v[10:13], v[174:177], v[220:223], v[10:13]
	v_mfma_f32_16x16x32_bf16 v[4:7], v[184:187], v[220:223], v[4:7]
	s_setprio 0
	s_barrier
	s_add_i32 s82, 0, 0x18000
	v_add_u32_e32 v3, s82, v183
	s_add_i32 s83, 0, 0x1c000
	ds_read_b128 v[154:157], v3
	ds_read_b128 v[158:161], v3 offset:1024
	ds_read_b128 v[162:165], v3 offset:2048
	ds_read_b128 v[166:169], v3 offset:3072
	v_add_u32_e32 v3, s83, v183
	ds_read_b128 v[170:173], v3
	ds_read_b128 v[174:177], v3 offset:1024
	ds_read_b128 v[178:181], v3 offset:2048
	ds_read_b128 v[184:187], v3 offset:3072
	s_add_u32 s52, s52, 0x100000
	s_addc_u32 s53, s53, 0
	s_mov_b32 m0, s60
	ds_read_b128 v[188:191], v211 offset:32768
	ds_read_b128 v[192:195], v211 offset:33792
	ds_read_b128 v[196:199], v211 offset:34816
	ds_read_b128 v[200:203], v211 offset:35840
	ds_read_b128 v[204:207], v211 offset:36864
	ds_read_b128 v[212:215], v211 offset:37888
	ds_read_b128 v[216:219], v211 offset:38912
	ds_read_b128 v[220:223], v211 offset:39936
	global_load_lds_dwordx4 v134, s[52:53]
	s_mov_b32 m0, s61
	s_nop 0
	global_load_lds_dwordx4 v136, s[52:53]
	s_waitcnt vmcnt(8)
	s_waitcnt lgkmcnt(0)
	s_barrier
	s_setprio 1
	s_waitcnt lgkmcnt(0)
	v_mfma_f32_16x16x32_bf16 v[130:133], v[154:157], v[188:191], v[130:133]
	v_mfma_f32_16x16x32_bf16 v[126:129], v[162:165], v[188:191], v[126:129]
	v_mfma_f32_16x16x32_bf16 v[114:117], v[154:157], v[196:199], v[114:117]
	v_mfma_f32_16x16x32_bf16 v[110:113], v[162:165], v[196:199], v[110:113]
	v_mfma_f32_16x16x32_bf16 v[98:101], v[154:157], v[204:207], v[98:101]
	v_mfma_f32_16x16x32_bf16 v[94:97], v[162:165], v[204:207], v[94:97]
	v_mfma_f32_16x16x32_bf16 v[82:85], v[154:157], v[216:219], v[82:85]
	v_mfma_f32_16x16x32_bf16 v[78:81], v[162:165], v[216:219], v[78:81]
	v_mfma_f32_16x16x32_bf16 v[130:133], v[158:161], v[192:195], v[130:133]
	v_mfma_f32_16x16x32_bf16 v[126:129], v[166:169], v[192:195], v[126:129]
	v_mfma_f32_16x16x32_bf16 v[114:117], v[158:161], v[200:203], v[114:117]
	v_mfma_f32_16x16x32_bf16 v[110:113], v[166:169], v[200:203], v[110:113]
	v_mfma_f32_16x16x32_bf16 v[98:101], v[158:161], v[212:215], v[98:101]
	v_mfma_f32_16x16x32_bf16 v[94:97], v[166:169], v[212:215], v[94:97]
	v_mfma_f32_16x16x32_bf16 v[82:85], v[158:161], v[220:223], v[82:85]
	v_mfma_f32_16x16x32_bf16 v[78:81], v[166:169], v[220:223], v[78:81]
	s_setprio 0
	s_setprio 1
	v_mfma_f32_16x16x32_bf16 v[122:125], v[170:173], v[188:191], v[122:125]
	v_mfma_f32_16x16x32_bf16 v[118:121], v[178:181], v[188:191], v[118:121]
	v_mfma_f32_16x16x32_bf16 v[106:109], v[170:173], v[196:199], v[106:109]
	v_mfma_f32_16x16x32_bf16 v[102:105], v[178:181], v[196:199], v[102:105]
	v_mfma_f32_16x16x32_bf16 v[90:93], v[170:173], v[204:207], v[90:93]
	v_mfma_f32_16x16x32_bf16 v[86:89], v[178:181], v[204:207], v[86:89]
	v_mfma_f32_16x16x32_bf16 v[74:77], v[170:173], v[216:219], v[74:77]
	v_mfma_f32_16x16x32_bf16 v[70:73], v[178:181], v[216:219], v[70:73]
	v_mfma_f32_16x16x32_bf16 v[122:125], v[174:177], v[192:195], v[122:125]
	v_mfma_f32_16x16x32_bf16 v[118:121], v[184:187], v[192:195], v[118:121]
	v_mfma_f32_16x16x32_bf16 v[106:109], v[174:177], v[200:203], v[106:109]
	v_mfma_f32_16x16x32_bf16 v[102:105], v[184:187], v[200:203], v[102:105]
	v_mfma_f32_16x16x32_bf16 v[90:93], v[174:177], v[212:215], v[90:93]
	v_mfma_f32_16x16x32_bf16 v[86:89], v[184:187], v[212:215], v[86:89]
	v_mfma_f32_16x16x32_bf16 v[74:77], v[174:177], v[220:223], v[74:77]
	v_mfma_f32_16x16x32_bf16 v[70:73], v[184:187], v[220:223], v[70:73]
	s_setprio 0
	s_barrier
; #define PG8_STAGE(bufoff, gbase, voff) do { _Pragma("unroll") for (int _i = 0; _i < 2; ++_i) \
;         __builtin_amdgcn_global_load_lds((const unsigned*)((const char*)(gbase) + (voff)[_i]), (PG8_LAS unsigned*)(lds + (bufoff) + ldsw + _i * 8192), 16, 0, 0); } while (0)
; #define PG8_LDA(dst, b, h) do { _Pragma("unroll") for (int m = 0; m < 4; ++m) _Pragma("unroll") for (int k = 0; k < 2; ++k) dst[m][k] = *(const PG8_LAS bf16x8*)(lds + PG8_SA(b, h) + aoff + m * 2048 + k * 1024); } while (0)
; #define PG8_WAIT_V(n) asm volatile("s_waitcnt vmcnt(" #n ")" ::: "memory")
; #define PG8_BAR __builtin_amdgcn_s_barrier()
; template <class Epi, class Sched, bool ALIGN_EPI = false, bool SP2 = false>
; __device__ __forceinline__ void gemm_phase(PG8_LAS unsigned char* lds, const Gemm g, const Sched& S, const Epi& E) {
;     ...
;         for (int t = 0; t < ntc; t += 2) {
;             if constexpr (Epi::MID) { if (ntc == nt && t == (nt >> 1)) E.mid(acc, cur, wr, wc, fr, fq); }
;             const bool last = (t == ntc - 2);
;             const char* a1 = cA + (size_t)(t + 1) * kstep;
;             const char* a2 = last ? nA : cA + (size_t)(t + 2) * kstep; const char* b2 = last ? nB : cB + (size_t)(t + 2) * kstep;
;             const char* a3 = a2 + kstep; const char* b3 = b2 + kstep;
;             if (last && has_next) S.a_ready(nxt);
;             if constexpr (SP2) {
;             PG8_LDB(B0, 0, 0); PG8_LDB(B1, 0, 1); PG8_SCHED; PG8_LDA(At, 0, 0); PG8_STAGE(PG8_SA(1, 1), a1 + hstep, voffA);
;             PG8_WAIT_V(8); PG8_WAIT_L(0); PG8_BAR; PG8_MMA(0, 0, At, B0); PG8_MMA(0, 1, At, B1); PG8_BAR; PG8_SCHED;
;             PG8_LDA(At, 0, 1); PG8_STAGE(PG8_SB(0, 0), b2, voffB); PG8_STAGE(PG8_SB(0, 1), b2 + hstep, voffB); PG8_STAGE(PG8_SA(0, 0), a2, voffA);
;             PG8_WAIT_V(8); PG8_WAIT_L(0); PG8_BAR; PG8_MMA(1, 0, At, B0); PG8_MMA(1, 1, At, B1); PG8_BAR; PG8_SCHED;
;             PG8_LDB(B0, 1, 0); PG8_LDB(B1, 1, 1); PG8_SCHED; PG8_LDA(At, 1, 0); PG8_STAGE(PG8_SA(0, 1), a2 + hstep, voffA);
;             PG8_WAIT_V(8); PG8_WAIT_L(0); PG8_BAR; PG8_MMA(0, 0, At, B0); PG8_MMA(0, 1, At, B1); PG8_BAR; PG8_SCHED;
;             PG8_LDA(At, 1, 1); PG8_STAGE(PG8_SB(1, 0), b3, voffB); PG8_STAGE(PG8_SB(1, 1), b3 + hstep, voffB); PG8_STAGE(PG8_SA(1, 0), a3, voffA);
;             PG8_WAIT_V(8); PG8_WAIT_L(0); PG8_BAR; PG8_MMA(1, 0, At, B0); PG8_MMA(1, 1, At, B1); PG8_BAR; PG8_SCHED;
	s_add_u32 s100, s52, 0xfff00080
	s_addc_u32 s101, s53, -1
	s_add_u32 s98, s50, 0x80
	s_addc_u32 s99, s51, 0
	s_add_i32 s52, s82, s55
	s_mov_b32 m0, s52
	ds_read_b128 v[188:191], v211 offset:49152
	ds_read_b128 v[192:195], v211 offset:50176
	ds_read_b128 v[196:199], v211 offset:51200
	ds_read_b128 v[200:203], v211 offset:52224
	ds_read_b128 v[204:207], v211 offset:53248
	ds_read_b128 v[212:215], v211 offset:54272
	ds_read_b128 v[216:219], v211 offset:55296
	ds_read_b128 v[220:223], v211 offset:56320
	global_load_lds_dwordx4 v134, s[98:99]
	s_add_i32 m0, s52, 0x2000
	s_add_u32 s50, s50, 0x100080
	s_addc_u32 s51, s51, 0
	s_add_i32 s52, s83, s55
	global_load_lds_dwordx4 v136, s[98:99]
	s_mov_b32 m0, s52
	s_nop 0
	global_load_lds_dwordx4 v134, s[50:51]
	s_add_i32 m0, s52, 0x2000
	s_nop 0
	global_load_lds_dwordx4 v136, s[50:51]
	s_mov_b32 m0, s63
	s_nop 0
	global_load_lds_dwordx4 v134, s[100:101]
	s_mov_b32 m0, s64
	s_nop 0
	global_load_lds_dwordx4 v136, s[100:101]
	s_waitcnt vmcnt(8)
	s_waitcnt lgkmcnt(0)
	s_barrier
	s_setprio 1
	s_waitcnt lgkmcnt(0)
	v_mfma_f32_16x16x32_bf16 v[66:69], v[154:157], v[188:191], v[66:69]
	v_mfma_f32_16x16x32_bf16 v[62:65], v[162:165], v[188:191], v[62:65]
	v_mfma_f32_16x16x32_bf16 v[50:53], v[154:157], v[196:199], v[50:53]
	v_mfma_f32_16x16x32_bf16 v[46:49], v[162:165], v[196:199], v[46:49]
	v_mfma_f32_16x16x32_bf16 v[34:37], v[154:157], v[204:207], v[34:37]
	v_mfma_f32_16x16x32_bf16 v[30:33], v[162:165], v[204:207], v[30:33]
	v_mfma_f32_16x16x32_bf16 v[18:21], v[154:157], v[216:219], v[18:21]
	v_mfma_f32_16x16x32_bf16 v[14:17], v[162:165], v[216:219], v[14:17]
	v_mfma_f32_16x16x32_bf16 v[66:69], v[158:161], v[192:195], v[66:69]
	v_mfma_f32_16x16x32_bf16 v[62:65], v[166:169], v[192:195], v[62:65]
	v_mfma_f32_16x16x32_bf16 v[50:53], v[158:161], v[200:203], v[50:53]
	v_mfma_f32_16x16x32_bf16 v[46:49], v[166:169], v[200:203], v[46:49]
	v_mfma_f32_16x16x32_bf16 v[34:37], v[158:161], v[212:215], v[34:37]
	v_mfma_f32_16x16x32_bf16 v[30:33], v[166:169], v[212:215], v[30:33]
	v_mfma_f32_16x16x32_bf16 v[18:21], v[158:161], v[220:223], v[18:21]
	v_mfma_f32_16x16x32_bf16 v[14:17], v[166:169], v[220:223], v[14:17]
	s_setprio 0
	s_setprio 1
	v_mfma_f32_16x16x32_bf16 v[58:61], v[170:173], v[188:191], v[58:61]
	v_mfma_f32_16x16x32_bf16 v[54:57], v[178:181], v[188:191], v[54:57]
	v_mfma_f32_16x16x32_bf16 v[42:45], v[170:173], v[196:199], v[42:45]
	v_mfma_f32_16x16x32_bf16 v[38:41], v[178:181], v[196:199], v[38:41]
	v_mfma_f32_16x16x32_bf16 v[26:29], v[170:173], v[204:207], v[26:29]
	v_mfma_f32_16x16x32_bf16 v[22:25], v[178:181], v[204:207], v[22:25]
	v_mfma_f32_16x16x32_bf16 v[8:11], v[170:173], v[216:219], v[10:13]
	v_mfma_f32_16x16x32_bf16 v[4:7], v[178:181], v[216:219], v[4:7]
	v_mfma_f32_16x16x32_bf16 v[58:61], v[174:177], v[192:195], v[58:61]
	v_mfma_f32_16x16x32_bf16 v[54:57], v[184:187], v[192:195], v[54:57]
	v_mfma_f32_16x16x32_bf16 v[42:45], v[174:177], v[200:203], v[42:45]
	v_mfma_f32_16x16x32_bf16 v[38:41], v[184:187], v[200:203], v[38:41]
	v_mfma_f32_16x16x32_bf16 v[26:29], v[174:177], v[212:215], v[26:29]
	v_mfma_f32_16x16x32_bf16 v[22:25], v[184:187], v[212:215], v[22:25]
	v_mfma_f32_16x16x32_bf16 v[10:13], v[174:177], v[220:223], v[8:11]
	v_mfma_f32_16x16x32_bf16 v[6:9], v[184:187], v[220:223], v[4:7]
	s_setprio 0
	s_barrier
	s_add_u32 s46, s46, 0x100
	s_addc_u32 s47, s47, 0
	s_cmp_ge_i32 s81, s77
	s_cbranch_scc1 .LBB0_2489
	s_mov_b32 s50, s81
	s_branch .LBB0_2485

; #define PG8_STAGE(bufoff, gbase, voff) do { _Pragma("unroll") for (int _i = 0; _i < 2; ++_i) \
;         __builtin_amdgcn_global_load_lds((const unsigned*)((const char*)(gbase) + (voff)[_i]), (PG8_LAS unsigned*)(lds + (bufoff) + ldsw + _i * 8192), 16, 0, 0); } while (0)
; #define PG8_LDA(dst, b, h) do { _Pragma("unroll") for (int m = 0; m < 4; ++m) _Pragma("unroll") for (int k = 0; k < 2; ++k) dst[m][k] = *(const PG8_LAS bf16x8*)(lds + PG8_SA(b, h) + aoff + m * 2048 + k * 1024); } while (0)
; #define PG8_LDB(dst, b, h) do { _Pragma("unroll") for (int n = 0; n < 2; ++n) _Pragma("unroll") for (int k = 0; k < 2; ++k) dst[n][k] = *(const PG8_LAS bf16x8*)(lds + PG8_SB(b, h) + boff + n * 2048 + k * 1024); } while (0)
; #define PG8_MMA(ai, bj, At, Bt) do { __builtin_amdgcn_s_setprio(1); _Pragma("unroll") for (int m = 0; m < 4; ++m) _Pragma("unroll") for (int n = 0; n < 2; ++n) _Pragma("unroll") for (int k = 0; k < 2; ++k) \
;         acc[ai][bj][m][n] = __builtin_amdgcn_mfma_f32_16x16x32_bf16(Bt[n][k], At[m][k], acc[ai][bj][m][n], 0, 0, 0); __builtin_amdgcn_s_setprio(0); } while (0)
; #define PG8_WAIT_V(n) asm volatile("s_waitcnt vmcnt(" #n ")" ::: "memory")
; #define PG8_WAIT_L(n) asm volatile("s_waitcnt lgkmcnt(" #n ")" ::: "memory")
; #define PG8_BAR __builtin_amdgcn_s_barrier()
; #define PG8_SCHED __builtin_amdgcn_sched_barrier(0)
; template <class Epi, class Sched, bool ALIGN_EPI = false, bool SP2 = false>
; __device__ __forceinline__ void gemm_phase(PG8_LAS unsigned char* lds, const Gemm g, const Sched& S, const Epi& E) {
;     ...
;             if constexpr (SP2) {
;             PG8_LDB(B0, 0, 0); PG8_LDB(B1, 0, 1); PG8_SCHED; PG8_LDA(At, 0, 0); PG8_STAGE(PG8_SA(1, 1), a1 + hstep, voffA);
;             PG8_WAIT_V(8); PG8_WAIT_L(0); PG8_BAR; PG8_MMA(0, 0, At, B0); PG8_MMA(0, 1, At, B1); PG8_BAR; PG8_SCHED;
;             PG8_LDA(At, 0, 1); PG8_STAGE(PG8_SB(0, 0), b2, voffB); PG8_STAGE(PG8_SB(0, 1), b2 + hstep, voffB); PG8_STAGE(PG8_SA(0, 0), a2, voffA);
;             PG8_WAIT_V(8); PG8_WAIT_L(0); PG8_BAR; PG8_MMA(1, 0, At, B0); PG8_MMA(1, 1, At, B1); PG8_BAR; PG8_SCHED;
;             PG8_LDB(B0, 1, 0); PG8_LDB(B1, 1, 1); PG8_SCHED; PG8_LDA(At, 1, 0); PG8_STAGE(PG8_SA(0, 1), a2 + hstep, voffA);
;             PG8_WAIT_V(8); PG8_WAIT_L(0); PG8_BAR; PG8_MMA(0, 0, At, B0); PG8_MMA(0, 1, At, B1); PG8_BAR; PG8_SCHED;
.LBB0_3522:
	ds_read_b128 v[144:147], v177
	ds_read_b128 v[148:151], v177 offset:1024
	ds_read_b128 v[152:155], v177 offset:2048
	ds_read_b128 v[156:159], v177 offset:3072
	ds_read_b128 v[160:163], v178
	ds_read_b128 v[164:167], v178 offset:1024
	ds_read_b128 v[168:171], v178 offset:2048
	ds_read_b128 v[172:175], v178 offset:3072
	s_add_u32 s40, s38, 0x100
	s_addc_u32 s41, s39, 0
	s_cmp_eq_u32 s69, s71
	s_cselect_b32 s45, s35, s41
	s_cselect_b32 s44, s34, s40
	s_cselect_b32 s43, s37, s70
	s_cselect_b32 s42, s36, s31
	s_add_i32 m0, s51, 0xc000
	ds_read_b128 v[180:183], v179
	ds_read_b128 v[184:187], v179 offset:1024
	ds_read_b128 v[188:191], v179 offset:2048
	ds_read_b128 v[192:195], v179 offset:3072
	ds_read_b128 v[196:199], v179 offset:4096
	ds_read_b128 v[200:203], v179 offset:5120
	ds_read_b128 v[204:207], v179 offset:6144
	ds_read_b128 v[208:211], v179 offset:7168
	global_load_lds_dwordx4 v138, s[38:39]
	s_add_i32 m0, s51, 0xe000
	s_nop 0
	global_load_lds_dwordx4 v140, s[38:39]
	s_waitcnt vmcnt(8)
	s_waitcnt lgkmcnt(0)
	s_barrier
	s_setprio 1
	s_waitcnt lgkmcnt(0)
	v_mfma_f32_16x16x32_bf16 v[126:129], v[144:147], v[180:183], v[126:129]
	v_mfma_f32_16x16x32_bf16 v[122:125], v[152:155], v[180:183], v[122:125]
	v_mfma_f32_16x16x32_bf16 v[110:113], v[144:147], v[188:191], v[110:113]
	v_mfma_f32_16x16x32_bf16 v[106:109], v[152:155], v[188:191], v[106:109]
	v_mfma_f32_16x16x32_bf16 v[94:97], v[144:147], v[196:199], v[94:97]
	v_mfma_f32_16x16x32_bf16 v[90:93], v[152:155], v[196:199], v[90:93]
	v_mfma_f32_16x16x32_bf16 v[78:81], v[144:147], v[204:207], v[78:81]
	v_mfma_f32_16x16x32_bf16 v[74:77], v[152:155], v[204:207], v[74:77]
	v_mfma_f32_16x16x32_bf16 v[126:129], v[148:151], v[184:187], v[126:129]
	v_mfma_f32_16x16x32_bf16 v[122:125], v[156:159], v[184:187], v[122:125]
	v_mfma_f32_16x16x32_bf16 v[110:113], v[148:151], v[192:195], v[110:113]
	v_mfma_f32_16x16x32_bf16 v[106:109], v[156:159], v[192:195], v[106:109]
	v_mfma_f32_16x16x32_bf16 v[94:97], v[148:151], v[200:203], v[94:97]
	v_mfma_f32_16x16x32_bf16 v[90:93], v[156:159], v[200:203], v[90:93]
	v_mfma_f32_16x16x32_bf16 v[78:81], v[148:151], v[208:211], v[78:81]
	v_mfma_f32_16x16x32_bf16 v[74:77], v[156:159], v[208:211], v[74:77]
	s_setprio 0
	s_setprio 1
	v_mfma_f32_16x16x32_bf16 v[118:121], v[160:163], v[180:183], v[118:121]
	v_mfma_f32_16x16x32_bf16 v[114:117], v[168:171], v[180:183], v[114:117]
	v_mfma_f32_16x16x32_bf16 v[102:105], v[160:163], v[188:191], v[102:105]
	v_mfma_f32_16x16x32_bf16 v[98:101], v[168:171], v[188:191], v[98:101]
	v_mfma_f32_16x16x32_bf16 v[86:89], v[160:163], v[196:199], v[86:89]
	v_mfma_f32_16x16x32_bf16 v[82:85], v[168:171], v[196:199], v[82:85]
	v_mfma_f32_16x16x32_bf16 v[70:73], v[160:163], v[204:207], v[70:73]
	v_mfma_f32_16x16x32_bf16 v[66:69], v[168:171], v[204:207], v[66:69]
	v_mfma_f32_16x16x32_bf16 v[118:121], v[164:167], v[184:187], v[118:121]
	v_mfma_f32_16x16x32_bf16 v[114:117], v[172:175], v[184:187], v[114:117]
	v_mfma_f32_16x16x32_bf16 v[102:105], v[164:167], v[192:195], v[102:105]
	v_mfma_f32_16x16x32_bf16 v[98:101], v[172:175], v[192:195], v[98:101]
	v_mfma_f32_16x16x32_bf16 v[86:89], v[164:167], v[200:203], v[86:89]
	v_mfma_f32_16x16x32_bf16 v[82:85], v[172:175], v[200:203], v[82:85]
	v_mfma_f32_16x16x32_bf16 v[70:73], v[164:167], v[208:211], v[70:73]
	v_mfma_f32_16x16x32_bf16 v[66:69], v[172:175], v[208:211], v[66:69]
	s_setprio 0
	s_barrier
	s_add_i32 s38, s63, s50
	s_mov_b32 m0, s38
	ds_read_b128 v[180:183], v179 offset:16384
	ds_read_b128 v[184:187], v179 offset:17408
	ds_read_b128 v[188:191], v179 offset:18432
	ds_read_b128 v[192:195], v179 offset:19456
	ds_read_b128 v[196:199], v179 offset:20480
	ds_read_b128 v[200:203], v179 offset:21504
	ds_read_b128 v[204:207], v179 offset:22528
	ds_read_b128 v[208:211], v179 offset:23552
	global_load_lds_dwordx4 v130, s[42:43]
	s_add_i32 m0, s38, 0x2000
	s_add_u32 s38, s42, 0x300000
	s_addc_u32 s39, s43, 0
	s_add_i32 s58, s64, s50
	global_load_lds_dwordx4 v132, s[42:43]
	s_mov_b32 m0, s58
	s_nop 0
	global_load_lds_dwordx4 v130, s[38:39]
	s_add_i32 m0, s58, 0x2000
	s_nop 0
	global_load_lds_dwordx4 v132, s[38:39]
	s_mov_b32 m0, s51
	s_nop 0
	global_load_lds_dwordx4 v130, s[44:45]
	s_mov_b32 m0, s52
	s_nop 0
	global_load_lds_dwordx4 v132, s[44:45]
	s_waitcnt vmcnt(8)
	s_waitcnt lgkmcnt(0)
	s_barrier
	s_setprio 1
	s_waitcnt lgkmcnt(0)
	v_mfma_f32_16x16x32_bf16 v[62:65], v[144:147], v[180:183], v[62:65]
	v_mfma_f32_16x16x32_bf16 v[58:61], v[152:155], v[180:183], v[58:61]
	v_mfma_f32_16x16x32_bf16 v[46:49], v[144:147], v[188:191], v[46:49]
	v_mfma_f32_16x16x32_bf16 v[42:45], v[152:155], v[188:191], v[42:45]
	v_mfma_f32_16x16x32_bf16 v[30:33], v[144:147], v[196:199], v[30:33]
	v_mfma_f32_16x16x32_bf16 v[26:29], v[152:155], v[196:199], v[26:29]
	v_mfma_f32_16x16x32_bf16 v[14:17], v[144:147], v[204:207], v[14:17]
	v_mfma_f32_16x16x32_bf16 v[10:13], v[152:155], v[204:207], v[10:13]
	v_mfma_f32_16x16x32_bf16 v[62:65], v[148:151], v[184:187], v[62:65]
	v_mfma_f32_16x16x32_bf16 v[58:61], v[156:159], v[184:187], v[58:61]
	v_mfma_f32_16x16x32_bf16 v[46:49], v[148:151], v[192:195], v[46:49]
	v_mfma_f32_16x16x32_bf16 v[42:45], v[156:159], v[192:195], v[42:45]
	v_mfma_f32_16x16x32_bf16 v[30:33], v[148:151], v[200:203], v[30:33]
	v_mfma_f32_16x16x32_bf16 v[26:29], v[156:159], v[200:203], v[26:29]
	v_mfma_f32_16x16x32_bf16 v[14:17], v[148:151], v[208:211], v[14:17]
	v_mfma_f32_16x16x32_bf16 v[10:13], v[156:159], v[208:211], v[10:13]
	s_setprio 0
	s_setprio 1
	v_mfma_f32_16x16x32_bf16 v[54:57], v[160:163], v[180:183], v[54:57]
	v_mfma_f32_16x16x32_bf16 v[50:53], v[168:171], v[180:183], v[50:53]
	v_mfma_f32_16x16x32_bf16 v[38:41], v[160:163], v[188:191], v[38:41]
	v_mfma_f32_16x16x32_bf16 v[34:37], v[168:171], v[188:191], v[34:37]
	v_mfma_f32_16x16x32_bf16 v[22:25], v[160:163], v[196:199], v[22:25]
	v_mfma_f32_16x16x32_bf16 v[18:21], v[168:171], v[196:199], v[18:21]
	v_mfma_f32_16x16x32_bf16 v[6:9], v[160:163], v[204:207], v[6:9]
	v_mfma_f32_16x16x32_bf16 v[2:5], v[168:171], v[204:207], v[2:5]
	v_mfma_f32_16x16x32_bf16 v[54:57], v[164:167], v[184:187], v[54:57]
	v_mfma_f32_16x16x32_bf16 v[50:53], v[172:175], v[184:187], v[50:53]
	v_mfma_f32_16x16x32_bf16 v[38:41], v[164:167], v[192:195], v[38:41]
	v_mfma_f32_16x16x32_bf16 v[34:37], v[172:175], v[192:195], v[34:37]
	v_mfma_f32_16x16x32_bf16 v[22:25], v[164:167], v[200:203], v[22:25]
	v_mfma_f32_16x16x32_bf16 v[18:21], v[172:175], v[200:203], v[18:21]
	v_mfma_f32_16x16x32_bf16 v[6:9], v[164:167], v[208:211], v[6:9]
	v_mfma_f32_16x16x32_bf16 v[2:5], v[172:175], v[208:211], v[2:5]
	s_setprio 0
	s_barrier
; #define PG8_STAGE(bufoff, gbase, voff) do { _Pragma("unroll") for (int _i = 0; _i < 2; ++_i) \
;         __builtin_amdgcn_global_load_lds((const unsigned*)((const char*)(gbase) + (voff)[_i]), (PG8_LAS unsigned*)(lds + (bufoff) + ldsw + _i * 8192), 16, 0, 0); } while (0)
; #define PG8_LDA(dst, b, h) do { _Pragma("unroll") for (int m = 0; m < 4; ++m) _Pragma("unroll") for (int k = 0; k < 2; ++k) dst[m][k] = *(const PG8_LAS bf16x8*)(lds + PG8_SA(b, h) + aoff + m * 2048 + k * 1024); } while (0)
; #define PG8_LDB(dst, b, h) do { _Pragma("unroll") for (int n = 0; n < 2; ++n) _Pragma("unroll") for (int k = 0; k < 2; ++k) dst[n][k] = *(const PG8_LAS bf16x8*)(lds + PG8_SB(b, h) + boff + n * 2048 + k * 1024); } while (0)
; #define PG8_MMA(ai, bj, At, Bt) do { __builtin_amdgcn_s_setprio(1); _Pragma("unroll") for (int m = 0; m < 4; ++m) _Pragma("unroll") for (int n = 0; n < 2; ++n) _Pragma("unroll") for (int k = 0; k < 2; ++k) \
;         acc[ai][bj][m][n] = __builtin_amdgcn_mfma_f32_16x16x32_bf16(Bt[n][k], At[m][k], acc[ai][bj][m][n], 0, 0, 0); __builtin_amdgcn_s_setprio(0); } while (0)
; #define PG8_WAIT_V(n) asm volatile("s_waitcnt vmcnt(" #n ")" ::: "memory")
; #define PG8_WAIT_L(n) asm volatile("s_waitcnt lgkmcnt(" #n ")" ::: "memory")
; #define PG8_BAR __builtin_amdgcn_s_barrier()
; #define PG8_SCHED __builtin_amdgcn_sched_barrier(0)
;     __device__ __forceinline__ void operator()(const f32x4 (&acc)[2][2][4][2], const Unit& u, int wr, int wc, int fr, int fq) const {
;     ...
;         if (u.ntu != 192) {
; template <class Epi, class Sched, bool ALIGN_EPI = false, bool SP2 = false>
; __device__ __forceinline__ void gemm_phase(PG8_LAS unsigned char* lds, const Gemm g, const Sched& S, const Epi& E) {
;     ...
;             PG8_LDB(B0, 1, 0); PG8_LDB(B1, 1, 1); PG8_SCHED; PG8_LDA(At, 1, 0); PG8_STAGE(PG8_SA(0, 1), a2 + hstep, voffA);
;             PG8_WAIT_V(8); PG8_WAIT_L(0); PG8_BAR; PG8_MMA(0, 0, At, B0); PG8_MMA(0, 1, At, B1); PG8_BAR; PG8_SCHED;
;             PG8_LDA(At, 1, 1); PG8_STAGE(PG8_SB(1, 0), b3, voffB); PG8_STAGE(PG8_SB(1, 1), b3 + hstep, voffB); PG8_STAGE(PG8_SA(1, 0), a3, voffA);
;             PG8_WAIT_V(8); PG8_WAIT_L(0); PG8_BAR; PG8_MMA(1, 0, At, B0); PG8_MMA(1, 1, At, B1); PG8_BAR; PG8_SCHED;
	s_add_i32 s58, 0, 0x18000
	v_add_u32_e32 v134, s58, v1
	s_add_i32 s59, 0, 0x1c000
	ds_read_b128 v[144:147], v134
	ds_read_b128 v[148:151], v134 offset:1024
	ds_read_b128 v[152:155], v134 offset:2048
	ds_read_b128 v[156:159], v134 offset:3072
	v_add_u32_e32 v134, s59, v1
	ds_read_b128 v[160:163], v134
	ds_read_b128 v[164:167], v134 offset:1024
	ds_read_b128 v[168:171], v134 offset:2048
	ds_read_b128 v[172:175], v134 offset:3072
	s_add_u32 s38, s44, 0x300000
	s_addc_u32 s39, s45, 0
	s_mov_b32 m0, s53
	ds_read_b128 v[180:183], v179 offset:32768
	ds_read_b128 v[184:187], v179 offset:33792
	ds_read_b128 v[188:191], v179 offset:34816
	ds_read_b128 v[192:195], v179 offset:35840
	ds_read_b128 v[196:199], v179 offset:36864
	ds_read_b128 v[200:203], v179 offset:37888
	ds_read_b128 v[204:207], v179 offset:38912
	ds_read_b128 v[208:211], v179 offset:39936
	global_load_lds_dwordx4 v130, s[38:39]
	s_mov_b32 m0, s54
	s_nop 0
	global_load_lds_dwordx4 v132, s[38:39]
	s_waitcnt vmcnt(8)
	s_waitcnt lgkmcnt(0)
	s_barrier
	s_setprio 1
	s_waitcnt lgkmcnt(0)
	v_mfma_f32_16x16x32_bf16 v[126:129], v[144:147], v[180:183], v[126:129]
	v_mfma_f32_16x16x32_bf16 v[122:125], v[152:155], v[180:183], v[122:125]
	v_mfma_f32_16x16x32_bf16 v[110:113], v[144:147], v[188:191], v[110:113]
	v_mfma_f32_16x16x32_bf16 v[106:109], v[152:155], v[188:191], v[106:109]
	v_mfma_f32_16x16x32_bf16 v[94:97], v[144:147], v[196:199], v[94:97]
	v_mfma_f32_16x16x32_bf16 v[90:93], v[152:155], v[196:199], v[90:93]
	v_mfma_f32_16x16x32_bf16 v[78:81], v[144:147], v[204:207], v[78:81]
	v_mfma_f32_16x16x32_bf16 v[74:77], v[152:155], v[204:207], v[74:77]
	v_mfma_f32_16x16x32_bf16 v[126:129], v[148:151], v[184:187], v[126:129]
	v_mfma_f32_16x16x32_bf16 v[122:125], v[156:159], v[184:187], v[122:125]
	v_mfma_f32_16x16x32_bf16 v[110:113], v[148:151], v[192:195], v[110:113]
	v_mfma_f32_16x16x32_bf16 v[106:109], v[156:159], v[192:195], v[106:109]
	v_mfma_f32_16x16x32_bf16 v[94:97], v[148:151], v[200:203], v[94:97]
	v_mfma_f32_16x16x32_bf16 v[90:93], v[156:159], v[200:203], v[90:93]
	v_mfma_f32_16x16x32_bf16 v[78:81], v[148:151], v[208:211], v[78:81]
	v_mfma_f32_16x16x32_bf16 v[74:77], v[156:159], v[208:211], v[74:77]
	s_setprio 0
	s_setprio 1
	v_mfma_f32_16x16x32_bf16 v[118:121], v[160:163], v[180:183], v[118:121]
	v_mfma_f32_16x16x32_bf16 v[114:117], v[168:171], v[180:183], v[114:117]
	v_mfma_f32_16x16x32_bf16 v[102:105], v[160:163], v[188:191], v[102:105]
	v_mfma_f32_16x16x32_bf16 v[98:101], v[168:171], v[188:191], v[98:101]
	v_mfma_f32_16x16x32_bf16 v[86:89], v[160:163], v[196:199], v[86:89]
	v_mfma_f32_16x16x32_bf16 v[82:85], v[168:171], v[196:199], v[82:85]
	v_mfma_f32_16x16x32_bf16 v[70:73], v[160:163], v[204:207], v[70:73]
	v_mfma_f32_16x16x32_bf16 v[66:69], v[168:171], v[204:207], v[66:69]
	v_mfma_f32_16x16x32_bf16 v[118:121], v[164:167], v[184:187], v[118:121]
	v_mfma_f32_16x16x32_bf16 v[114:117], v[172:175], v[184:187], v[114:117]
	v_mfma_f32_16x16x32_bf16 v[102:105], v[164:167], v[192:195], v[102:105]
	v_mfma_f32_16x16x32_bf16 v[98:101], v[172:175], v[192:195], v[98:101]
	v_mfma_f32_16x16x32_bf16 v[86:89], v[164:167], v[200:203], v[86:89]
	v_mfma_f32_16x16x32_bf16 v[82:85], v[172:175], v[200:203], v[82:85]
	v_mfma_f32_16x16x32_bf16 v[70:73], v[164:167], v[208:211], v[70:73]
	v_mfma_f32_16x16x32_bf16 v[66:69], v[172:175], v[208:211], v[66:69]
	s_setprio 0
	s_barrier
	s_add_i32 s38, s58, s50
	s_add_u32 s98, s42, 0x80
	s_addc_u32 s99, s43, 0
	s_add_u32 s100, s44, 0x80
	s_addc_u32 s101, s45, 0
	s_mov_b32 m0, s38
	ds_read_b128 v[180:183], v179 offset:49152
	ds_read_b128 v[184:187], v179 offset:50176
	ds_read_b128 v[188:191], v179 offset:51200
	ds_read_b128 v[192:195], v179 offset:52224
	ds_read_b128 v[196:199], v179 offset:53248
	ds_read_b128 v[200:203], v179 offset:54272
	ds_read_b128 v[204:207], v179 offset:55296
	ds_read_b128 v[208:211], v179 offset:56320
	global_load_lds_dwordx4 v130, s[98:99]
	s_add_i32 m0, s38, 0x2000
	s_add_u32 s38, s42, 0x300080
	s_addc_u32 s39, s43, 0
	s_add_i32 s42, s59, s50
	global_load_lds_dwordx4 v132, s[98:99]
	s_mov_b32 m0, s42
	s_nop 0
	global_load_lds_dwordx4 v130, s[38:39]
	s_add_i32 m0, s42, 0x2000
	s_nop 0
	global_load_lds_dwordx4 v132, s[38:39]
	s_mov_b32 m0, s57
	s_nop 0
	global_load_lds_dwordx4 v130, s[100:101]
	s_mov_b32 m0, s60
	s_nop 0
	global_load_lds_dwordx4 v132, s[100:101]
	s_waitcnt vmcnt(8)
	s_waitcnt lgkmcnt(0)
	s_barrier
	s_setprio 1
	s_waitcnt lgkmcnt(0)
	v_mfma_f32_16x16x32_bf16 v[62:65], v[144:147], v[180:183], v[62:65]
	v_mfma_f32_16x16x32_bf16 v[58:61], v[152:155], v[180:183], v[58:61]
	v_mfma_f32_16x16x32_bf16 v[46:49], v[144:147], v[188:191], v[46:49]
	v_mfma_f32_16x16x32_bf16 v[42:45], v[152:155], v[188:191], v[42:45]
	v_mfma_f32_16x16x32_bf16 v[30:33], v[144:147], v[196:199], v[30:33]
	v_mfma_f32_16x16x32_bf16 v[26:29], v[152:155], v[196:199], v[26:29]
	v_mfma_f32_16x16x32_bf16 v[14:17], v[144:147], v[204:207], v[14:17]
	v_mfma_f32_16x16x32_bf16 v[10:13], v[152:155], v[204:207], v[10:13]
	v_mfma_f32_16x16x32_bf16 v[62:65], v[148:151], v[184:187], v[62:65]
	v_mfma_f32_16x16x32_bf16 v[58:61], v[156:159], v[184:187], v[58:61]
	v_mfma_f32_16x16x32_bf16 v[46:49], v[148:151], v[192:195], v[46:49]
	v_mfma_f32_16x16x32_bf16 v[42:45], v[156:159], v[192:195], v[42:45]
	v_mfma_f32_16x16x32_bf16 v[30:33], v[148:151], v[200:203], v[30:33]
	v_mfma_f32_16x16x32_bf16 v[26:29], v[156:159], v[200:203], v[26:29]
	v_mfma_f32_16x16x32_bf16 v[14:17], v[148:151], v[208:211], v[14:17]
	v_mfma_f32_16x16x32_bf16 v[10:13], v[156:159], v[208:211], v[10:13]
	s_setprio 0
	s_setprio 1
	v_mfma_f32_16x16x32_bf16 v[54:57], v[160:163], v[180:183], v[54:57]
	v_mfma_f32_16x16x32_bf16 v[50:53], v[168:171], v[180:183], v[50:53]
	v_mfma_f32_16x16x32_bf16 v[38:41], v[160:163], v[188:191], v[38:41]
	v_mfma_f32_16x16x32_bf16 v[34:37], v[168:171], v[188:191], v[34:37]
	v_mfma_f32_16x16x32_bf16 v[22:25], v[160:163], v[196:199], v[22:25]
	v_mfma_f32_16x16x32_bf16 v[18:21], v[168:171], v[196:199], v[18:21]
	v_mfma_f32_16x16x32_bf16 v[6:9], v[160:163], v[204:207], v[6:9]
	v_mfma_f32_16x16x32_bf16 v[2:5], v[168:171], v[204:207], v[2:5]
	v_mfma_f32_16x16x32_bf16 v[54:57], v[164:167], v[184:187], v[54:57]
	v_mfma_f32_16x16x32_bf16 v[50:53], v[172:175], v[184:187], v[50:53]
	v_mfma_f32_16x16x32_bf16 v[38:41], v[164:167], v[192:195], v[38:41]
	v_mfma_f32_16x16x32_bf16 v[34:37], v[172:175], v[192:195], v[34:37]
	v_mfma_f32_16x16x32_bf16 v[22:25], v[164:167], v[200:203], v[22:25]
	v_mfma_f32_16x16x32_bf16 v[18:21], v[172:175], v[200:203], v[18:21]
	v_mfma_f32_16x16x32_bf16 v[6:9], v[164:167], v[208:211], v[6:9]
	v_mfma_f32_16x16x32_bf16 v[2:5], v[172:175], v[208:211], v[2:5]
	s_setprio 0
	s_barrier
	s_add_i32 s42, s71, 2
	s_add_u32 s31, s31, 0x100
	s_addc_u32 s70, s70, 0
	s_cmp_ge_i32 s71, s69
	s_mov_b64 s[38:39], s[40:41]
	s_mov_b32 s71, s42
	s_cbranch_scc0 .LBB0_3522
	s_and_b64 vcc, exec, s[20:21]
	s_cbranch_vccz .LBB0_3543
	s_barrier
	v_lshl_or_b32 v144, s5, 8, v176
	s_cmpk_eq_i32 s69, 0xc0
	s_mov_b64 s[38:39], -1
	s_cbranch_scc0 .LBB0_3544
